# norm loops: wave-wide sum of squares via DPP adds and permlane16 swap instead of five ds_swizzle round trips
# baseline (speedup 1.0000x reference)
.LBB0_442:
	s_or_b64 exec, exec, s[4:5]
	s_waitcnt vmcnt(0)
	v_mov_b32_e32 v53, v185
	v_min_i32_e32 v98, 0x8000, v32
	v_ashrrev_i32_e32 v98, 11, v98
	v_mul_hi_i32_i24_e32 v97, 0x6000, v98
	v_mul_i32_i24_e32 v96, 0x6000, v98
	v_lshl_add_u64 v[96:97], s[8:9], 0, v[96:97]
	s_mov_b64 s[4:5], 0x1000
	v_lshl_add_u64 v[94:95], v[96:97], 0, s[4:5]
	v_lshl_add_u64 v[94:95], v[94:95], 0, v[52:53]
	v_lshl_add_u64 v[96:97], v[96:97], 0, v[52:53]
	global_load_dwordx4 v[100:103], v[42:43], off
	global_load_dwordx4 v[104:107], v[42:43], off offset:1024
	global_load_dwordx4 v[108:111], v[42:43], off offset:2048
	global_load_dwordx4 v[112:115], v[42:43], off offset:3072
	global_load_dwordx4 v[116:119], v[94:95], off
	global_load_dwordx4 v[120:123], v[94:95], off offset:1024
	global_load_dwordx4 v[124:127], v[94:95], off offset:2048
	global_load_dwordx4 v[128:131], v[94:95], off offset:3072
	global_load_dwordx4 v[132:135], v[96:97], off
	global_load_dwordx4 v[136:139], v[96:97], off offset:1024
	global_load_dwordx4 v[140:143], v[96:97], off offset:2048
	global_load_dwordx4 v[144:147], v[96:97], off offset:3072
	v_min_i32_e32 v98, 0x8000, v62
	v_ashrrev_i32_e32 v98, 11, v98
	v_mul_hi_i32_i24_e32 v97, 0x6000, v98
	v_mul_i32_i24_e32 v96, 0x6000, v98
	v_lshl_add_u64 v[96:97], s[8:9], 0, v[96:97]
	s_mov_b64 s[4:5], 0x1000
	v_lshl_add_u64 v[94:95], v[96:97], 0, s[4:5]
	v_lshl_add_u64 v[94:95], v[94:95], 0, v[52:53]
	v_lshl_add_u64 v[96:97], v[96:97], 0, v[52:53]
	global_load_dwordx4 v[148:151], v[94:95], off
	global_load_dwordx4 v[152:155], v[94:95], off offset:1024
	global_load_dwordx4 v[156:159], v[94:95], off offset:2048
	global_load_dwordx4 v[160:163], v[94:95], off offset:3072
	global_load_dwordx4 v[164:167], v[96:97], off
	global_load_dwordx4 v[168:171], v[96:97], off offset:1024
	global_load_dwordx4 v[172:175], v[96:97], off offset:2048
	global_load_dwordx4 v[176:179], v[96:97], off offset:3072
	v_mul_f32_e32 v180, v29, v29
	v_mul_f32_e32 v182, v31, v31
	v_fmac_f32_e32 v180, v28, v28
	v_fmac_f32_e32 v182, v30, v30
	v_add_f32_e32 v180, v180, v182
	v_mul_f32_e32 v181, v25, v25
	v_mul_f32_e32 v182, v27, v27
	v_fmac_f32_e32 v181, v24, v24
	v_fmac_f32_e32 v182, v26, v26
	v_add_f32_e32 v181, v181, v182
	v_add_f32_e32 v180, v180, v181
	v_mul_f32_e32 v181, v21, v21
	v_mul_f32_e32 v182, v23, v23
	v_fmac_f32_e32 v181, v20, v20
	v_fmac_f32_e32 v182, v22, v22
	v_add_f32_e32 v181, v181, v182
	v_add_f32_e32 v180, v180, v181
	v_mul_f32_e32 v181, v17, v17
	v_mul_f32_e32 v182, v19, v19
	v_fmac_f32_e32 v181, v16, v16
	v_fmac_f32_e32 v182, v18, v18
	v_add_f32_e32 v181, v181, v182
	v_add_f32_e32 v180, v180, v181
	s_nop 1
	v_add_f32_dpp v180, v180, v180 quad_perm:[1,0,3,2] row_mask:0xf bank_mask:0xf
	s_nop 1
	v_add_f32_dpp v180, v180, v180 quad_perm:[2,3,0,1] row_mask:0xf bank_mask:0xf
	s_nop 1
	v_add_f32_dpp v180, v180, v180 row_half_mirror row_mask:0xf bank_mask:0xf
	s_nop 1
	v_add_f32_dpp v180, v180, v180 row_mirror row_mask:0xf bank_mask:0xf
	v_mov_b32_e32 v181, v180
	s_nop 1
	v_permlane16_swap_b32_e32 v180, v181
	v_add_f32_e32 v180, v180, v181
	v_mov_b32_e32 v181, v180
	s_nop 1
	v_permlane32_swap_b32_e32 v180, v181
	v_add_f32_e32 v180, v180, v181
	v_fmamk_f32 v180, v180, 0x3a800000, v245
	s_mov_b32 s4, 0xf800000
	v_cmp_gt_f32_e32 vcc, s4, v180
	v_mul_f32_e32 v181, 0x4f800000, v180
	s_nop 0
	v_cndmask_b32_e32 v180, v180, v181, vcc
	v_sqrt_f32_e32 v181, v180
	s_nop 0
	v_add_u32_e32 v182, -1, v181
	v_fma_f32 v186, -v182, v181, v180
	v_cmp_ge_f32_e64 s[4:5], 0, v186
	v_add_u32_e32 v186, 1, v181
	s_nop 0
	v_cndmask_b32_e64 v182, v181, v182, s[4:5]
	v_fma_f32 v181, -v186, v181, v180
	v_cmp_lt_f32_e64 s[4:5], 0, v181
	s_nop 1
	v_cndmask_b32_e64 v181, v182, v186, s[4:5]
	v_mul_f32_e32 v182, 0x37800000, v181
	v_cndmask_b32_e32 v181, v181, v182, vcc
	v_cmp_class_f32_e32 vcc, v180, v250
	s_nop 1
	v_cndmask_b32_e32 v180, v181, v180, vcc
	v_div_scale_f32 v181, s[4:5], v180, v180, 1.0
	v_rcp_f32_e32 v182, v181
	s_nop 0
	v_fma_f32 v186, -v181, v182, 1.0
	v_fmac_f32_e32 v182, v186, v182
	v_div_scale_f32 v186, vcc, 1.0, v180, 1.0
	v_mul_f32_e32 v188, v186, v182
	v_fma_f32 v189, -v181, v188, v186
	v_fmac_f32_e32 v188, v189, v182
	v_fma_f32 v181, -v181, v188, v186
	v_div_fmas_f32 v181, v181, v182, v188
	v_div_fixup_f32 v186, v181, v180, 1.0
	s_waitcnt vmcnt(0)
	v_pk_mul_f32 v[30:31], v[30:31], v[186:187] op_sel_hi:[1,0]
	v_pk_mul_f32 v[28:29], v[28:29], v[186:187] op_sel_hi:[1,0]
	v_pk_mul_f32 v[30:31], v[102:103], v[30:31]
	v_pk_mul_f32 v[28:29], v[100:101], v[28:29]
	v_pk_add_f32 v[116:117], v[116:117], 1.0 op_sel_hi:[1,0]
	v_pk_add_f32 v[118:119], v[118:119], 1.0 op_sel_hi:[1,0]
	v_pk_fma_f32 v[28:29], v[116:117], v[28:29], v[132:133]
	v_pk_fma_f32 v[30:31], v[118:119], v[30:31], v[134:135]
	v_cvt_pk_bf16_f32 v28, v28, v29
	v_cvt_pk_bf16_f32 v29, v30, v31
	global_store_dwordx2 v[50:51], v[28:29], off
	v_pk_mul_f32 v[26:27], v[26:27], v[186:187] op_sel_hi:[1,0]
	v_pk_mul_f32 v[24:25], v[24:25], v[186:187] op_sel_hi:[1,0]
	v_pk_mul_f32 v[26:27], v[106:107], v[26:27]
	v_pk_mul_f32 v[24:25], v[104:105], v[24:25]
	v_pk_add_f32 v[120:121], v[120:121], 1.0 op_sel_hi:[1,0]
	v_pk_add_f32 v[122:123], v[122:123], 1.0 op_sel_hi:[1,0]
	v_pk_fma_f32 v[24:25], v[120:121], v[24:25], v[136:137]
	v_pk_fma_f32 v[26:27], v[122:123], v[26:27], v[138:139]
	v_cvt_pk_bf16_f32 v24, v24, v25
	v_cvt_pk_bf16_f32 v25, v26, v27
	global_store_dwordx2 v[50:51], v[24:25], off offset:512
	v_pk_mul_f32 v[22:23], v[22:23], v[186:187] op_sel_hi:[1,0]
	v_pk_mul_f32 v[20:21], v[20:21], v[186:187] op_sel_hi:[1,0]
	v_pk_mul_f32 v[22:23], v[110:111], v[22:23]
	v_pk_mul_f32 v[20:21], v[108:109], v[20:21]
	v_pk_add_f32 v[124:125], v[124:125], 1.0 op_sel_hi:[1,0]
	v_pk_add_f32 v[126:127], v[126:127], 1.0 op_sel_hi:[1,0]
	v_pk_fma_f32 v[20:21], v[124:125], v[20:21], v[140:141]
	v_pk_fma_f32 v[22:23], v[126:127], v[22:23], v[142:143]
	v_cvt_pk_bf16_f32 v20, v20, v21
	v_cvt_pk_bf16_f32 v21, v22, v23
	global_store_dwordx2 v[50:51], v[20:21], off offset:1024
	v_pk_mul_f32 v[18:19], v[18:19], v[186:187] op_sel_hi:[1,0]
	v_pk_mul_f32 v[16:17], v[16:17], v[186:187] op_sel_hi:[1,0]
	v_pk_mul_f32 v[18:19], v[114:115], v[18:19]
	v_pk_mul_f32 v[16:17], v[112:113], v[16:17]
	v_pk_add_f32 v[128:129], v[128:129], 1.0 op_sel_hi:[1,0]
	v_pk_add_f32 v[130:131], v[130:131], 1.0 op_sel_hi:[1,0]
	v_pk_fma_f32 v[16:17], v[128:129], v[16:17], v[144:145]
	v_pk_fma_f32 v[18:19], v[130:131], v[18:19], v[146:147]
	v_cvt_pk_bf16_f32 v16, v16, v17
	v_cvt_pk_bf16_f32 v17, v18, v19
	global_store_dwordx2 v[50:51], v[16:17], off offset:1536
	s_and_saveexec_b64 s[4:5], s[2:3]
	s_cbranch_execz .LBB0_431
	v_mul_f32_e32 v180, v1, v1
	v_mul_f32_e32 v182, v3, v3
	v_fmac_f32_e32 v180, v0, v0
	v_fmac_f32_e32 v182, v2, v2
	v_add_f32_e32 v180, v180, v182
	v_mul_f32_e32 v181, v5, v5
	v_mul_f32_e32 v182, v7, v7
	v_fmac_f32_e32 v181, v4, v4
	v_fmac_f32_e32 v182, v6, v6
	v_add_f32_e32 v181, v181, v182
	v_add_f32_e32 v180, v180, v181
	v_mul_f32_e32 v181, v9, v9
	v_mul_f32_e32 v182, v11, v11
	v_fmac_f32_e32 v181, v8, v8
	v_fmac_f32_e32 v182, v10, v10
	v_add_f32_e32 v181, v181, v182
	v_add_f32_e32 v180, v180, v181
	v_mul_f32_e32 v181, v13, v13
	v_mul_f32_e32 v182, v15, v15
	v_fmac_f32_e32 v181, v12, v12
	v_fmac_f32_e32 v182, v14, v14
	v_add_f32_e32 v181, v181, v182
	v_add_f32_e32 v180, v180, v181
	s_nop 1
	v_add_f32_dpp v180, v180, v180 quad_perm:[1,0,3,2] row_mask:0xf bank_mask:0xf
	s_nop 1
	v_add_f32_dpp v180, v180, v180 quad_perm:[2,3,0,1] row_mask:0xf bank_mask:0xf
	s_nop 1
	v_add_f32_dpp v180, v180, v180 row_half_mirror row_mask:0xf bank_mask:0xf
	s_nop 1
	v_add_f32_dpp v180, v180, v180 row_mirror row_mask:0xf bank_mask:0xf
	v_mov_b32_e32 v181, v180
	s_nop 1
	v_permlane16_swap_b32_e32 v180, v181
	v_add_f32_e32 v180, v180, v181
	v_mov_b32_e32 v181, v180
	s_nop 1
	v_permlane32_swap_b32_e32 v180, v181
	v_add_f32_e32 v180, v180, v181
	v_fmamk_f32 v180, v180, 0x3a800000, v245
	s_mov_b32 s2, 0xf800000
	v_cmp_gt_f32_e32 vcc, s2, v180
	v_mul_f32_e32 v181, 0x4f800000, v180
	s_nop 0
	v_cndmask_b32_e32 v180, v180, v181, vcc
	v_sqrt_f32_e32 v181, v180
	s_nop 0
	v_add_u32_e32 v182, -1, v181
	v_fma_f32 v186, -v182, v181, v180
	v_cmp_ge_f32_e64 s[2:3], 0, v186
	v_add_u32_e32 v186, 1, v181
	s_nop 0
	v_cndmask_b32_e64 v182, v181, v182, s[2:3]
	v_fma_f32 v181, -v186, v181, v180
	v_cmp_lt_f32_e64 s[2:3], 0, v181
	s_nop 1
	v_cndmask_b32_e64 v181, v182, v186, s[2:3]
	v_mul_f32_e32 v182, 0x37800000, v181
	v_cndmask_b32_e32 v181, v181, v182, vcc
	v_cmp_class_f32_e32 vcc, v180, v250
	s_nop 1
	v_cndmask_b32_e32 v180, v181, v180, vcc
	v_div_scale_f32 v181, s[2:3], v180, v180, 1.0
	v_rcp_f32_e32 v182, v181
	s_nop 0
	v_fma_f32 v186, -v181, v182, 1.0
	v_fmac_f32_e32 v182, v186, v182
	v_div_scale_f32 v186, vcc, 1.0, v180, 1.0
	v_mul_f32_e32 v188, v186, v182
	v_fma_f32 v189, -v181, v188, v186
	v_fmac_f32_e32 v188, v189, v182
	v_fma_f32 v181, -v181, v188, v186
	v_div_fmas_f32 v181, v181, v182, v188
	v_div_fixup_f32 v186, v181, v180, 1.0
	v_lshlrev_b64 v[62:63], 11, v[62:63]
	v_lshl_add_u64 v[62:63], v[48:49], 0, v[62:63]
	v_pk_mul_f32 v[2:3], v[2:3], v[186:187] op_sel_hi:[1,0]
	v_pk_mul_f32 v[0:1], v[0:1], v[186:187] op_sel_hi:[1,0]
	v_pk_mul_f32 v[2:3], v[102:103], v[2:3]
	v_pk_mul_f32 v[0:1], v[100:101], v[0:1]
	v_pk_add_f32 v[148:149], v[148:149], 1.0 op_sel_hi:[1,0]
	v_pk_add_f32 v[150:151], v[150:151], 1.0 op_sel_hi:[1,0]
	v_pk_fma_f32 v[0:1], v[148:149], v[0:1], v[164:165]
	v_pk_fma_f32 v[2:3], v[150:151], v[2:3], v[166:167]
	v_cvt_pk_bf16_f32 v0, v0, v1
	v_cvt_pk_bf16_f32 v1, v2, v3
	global_store_dwordx2 v[62:63], v[0:1], off
	v_pk_mul_f32 v[6:7], v[6:7], v[186:187] op_sel_hi:[1,0]
	v_pk_mul_f32 v[4:5], v[4:5], v[186:187] op_sel_hi:[1,0]
	v_pk_mul_f32 v[6:7], v[106:107], v[6:7]
	v_pk_mul_f32 v[4:5], v[104:105], v[4:5]
	v_pk_add_f32 v[152:153], v[152:153], 1.0 op_sel_hi:[1,0]
	v_pk_add_f32 v[154:155], v[154:155], 1.0 op_sel_hi:[1,0]
	v_pk_fma_f32 v[4:5], v[152:153], v[4:5], v[168:169]
	v_pk_fma_f32 v[6:7], v[154:155], v[6:7], v[170:171]
	v_cvt_pk_bf16_f32 v4, v4, v5
	v_cvt_pk_bf16_f32 v5, v6, v7
	global_store_dwordx2 v[62:63], v[4:5], off offset:512
	v_pk_mul_f32 v[10:11], v[10:11], v[186:187] op_sel_hi:[1,0]
	v_pk_mul_f32 v[8:9], v[8:9], v[186:187] op_sel_hi:[1,0]
	v_pk_mul_f32 v[10:11], v[110:111], v[10:11]
	v_pk_mul_f32 v[8:9], v[108:109], v[8:9]
	v_pk_add_f32 v[156:157], v[156:157], 1.0 op_sel_hi:[1,0]
	v_pk_add_f32 v[158:159], v[158:159], 1.0 op_sel_hi:[1,0]
	v_pk_fma_f32 v[8:9], v[156:157], v[8:9], v[172:173]
	v_pk_fma_f32 v[10:11], v[158:159], v[10:11], v[174:175]
	v_cvt_pk_bf16_f32 v8, v8, v9
	v_cvt_pk_bf16_f32 v9, v10, v11
	global_store_dwordx2 v[62:63], v[8:9], off offset:1024
	v_pk_mul_f32 v[14:15], v[14:15], v[186:187] op_sel_hi:[1,0]
	v_pk_mul_f32 v[12:13], v[12:13], v[186:187] op_sel_hi:[1,0]
	v_pk_mul_f32 v[14:15], v[114:115], v[14:15]
	v_pk_mul_f32 v[12:13], v[112:113], v[12:13]
	v_pk_add_f32 v[160:161], v[160:161], 1.0 op_sel_hi:[1,0]
	v_pk_add_f32 v[162:163], v[162:163], 1.0 op_sel_hi:[1,0]
	v_pk_fma_f32 v[12:13], v[160:161], v[12:13], v[176:177]
	v_pk_fma_f32 v[14:15], v[162:163], v[14:15], v[178:179]
	v_cvt_pk_bf16_f32 v12, v12, v13
	v_cvt_pk_bf16_f32 v13, v14, v15
	global_store_dwordx2 v[62:63], v[12:13], off offset:1536
	s_branch .LBB0_431

.Lnm6_skip1:
	s_or_b64 exec, exec, s[2:3]
	v_lshl_add_u64 v[62:63], v[44:45], 0, v[38:39]
	v_add_co_u32_e32 v62, vcc, s17, v62
	s_nop 1
	v_addc_co_u32_e32 v63, vcc, 0, v63, vcc
	v_lshl_add_u64 v[64:65], v[42:43], 0, v[38:39]
	v_add_co_u32_e32 v64, vcc, s17, v64
	s_nop 1
	v_addc_co_u32_e32 v65, vcc, 0, v65, vcc
	s_waitcnt vmcnt(0)
	v_mul_f32_e32 v47, v29, v29
	v_mul_f32_e32 v51, v31, v31
	v_fmac_f32_e32 v47, v28, v28
	v_fmac_f32_e32 v51, v30, v30
	v_add_f32_e32 v47, v47, v51
	v_mul_f32_e32 v49, v25, v25
	v_mul_f32_e32 v51, v27, v27
	v_fmac_f32_e32 v49, v24, v24
	v_fmac_f32_e32 v51, v26, v26
	v_add_f32_e32 v49, v49, v51
	v_add_f32_e32 v47, v47, v49
	v_mul_f32_e32 v49, v21, v21
	v_mul_f32_e32 v51, v23, v23
	v_fmac_f32_e32 v49, v20, v20
	v_fmac_f32_e32 v51, v22, v22
	v_add_f32_e32 v49, v49, v51
	v_add_f32_e32 v47, v47, v49
	v_mul_f32_e32 v49, v17, v17
	v_mul_f32_e32 v51, v19, v19
	v_fmac_f32_e32 v49, v16, v16
	v_fmac_f32_e32 v51, v18, v18
	v_add_f32_e32 v49, v49, v51
	v_add_f32_e32 v47, v47, v49
	s_nop 1
	v_add_f32_dpp v47, v47, v47 quad_perm:[1,0,3,2] row_mask:0xf bank_mask:0xf
	s_nop 1
	v_add_f32_dpp v47, v47, v47 quad_perm:[2,3,0,1] row_mask:0xf bank_mask:0xf
	s_nop 1
	v_add_f32_dpp v47, v47, v47 row_half_mirror row_mask:0xf bank_mask:0xf
	s_nop 1
	v_add_f32_dpp v47, v47, v47 row_mirror row_mask:0xf bank_mask:0xf
	v_mov_b32_e32 v49, v47
	s_nop 1
	v_permlane16_swap_b32_e32 v47, v49
	v_add_f32_e32 v47, v47, v49
	v_mov_b32_e32 v49, v47
	s_nop 1
	v_permlane32_swap_b32_e32 v47, v49
	v_add_f32_e32 v47, v47, v49
	v_fmamk_f32 v47, v47, 0x3a800000, v245
	s_mov_b32 s2, 0xf800000
	v_cmp_gt_f32_e32 vcc, s2, v47
	v_mul_f32_e32 v49, 0x4f800000, v47
	s_nop 0
	v_cndmask_b32_e32 v47, v47, v49, vcc
	v_sqrt_f32_e32 v49, v47
	s_nop 0
	v_add_u32_e32 v51, -1, v49
	v_fma_f32 v52, -v51, v49, v47
	v_cmp_ge_f32_e64 s[2:3], 0, v52
	v_add_u32_e32 v52, 1, v49
	s_nop 0
	v_cndmask_b32_e64 v51, v49, v51, s[2:3]
	v_fma_f32 v49, -v52, v49, v47
	v_cmp_lt_f32_e64 s[2:3], 0, v49
	s_nop 1
	v_cndmask_b32_e64 v49, v51, v52, s[2:3]
	v_mul_f32_e32 v51, 0x37800000, v49
	v_cndmask_b32_e32 v49, v49, v51, vcc
	v_cmp_class_f32_e32 vcc, v47, v250
	s_nop 1
	v_cndmask_b32_e32 v47, v49, v47, vcc
	v_div_scale_f32 v49, s[2:3], v47, v47, 1.0
	v_rcp_f32_e32 v51, v49
	s_nop 0
	v_fma_f32 v52, -v49, v51, 1.0
	v_fmac_f32_e32 v51, v52, v51
	v_div_scale_f32 v52, vcc, 1.0, v47, 1.0
	v_mul_f32_e32 v66, v52, v51
	v_fma_f32 v67, -v49, v66, v52
	v_fmac_f32_e32 v66, v67, v51
	v_fma_f32 v49, -v49, v66, v52
	v_div_fmas_f32 v49, v49, v51, v66
	v_div_fixup_f32 v52, v49, v47, 1.0
	v_pk_mul_f32 v[30:31], v[30:31], v[52:53] op_sel_hi:[1,0]
	v_pk_mul_f32 v[28:29], v[28:29], v[52:53] op_sel_hi:[1,0]
	v_pk_mul_f32 v[30:31], v[72:73], v[30:31]
	v_pk_mul_f32 v[28:29], v[70:71], v[28:29]
	v_pk_add_f32 v[86:87], v[86:87], 1.0 op_sel_hi:[1,0]
	v_pk_add_f32 v[88:89], v[88:89], 1.0 op_sel_hi:[1,0]
	v_pk_fma_f32 v[28:29], v[86:87], v[28:29], v[102:103]
	v_pk_fma_f32 v[30:31], v[88:89], v[30:31], v[104:105]
	v_cvt_pk_bf16_f32 v28, v28, v29
	v_cvt_pk_bf16_f32 v29, v30, v31
	global_store_dwordx2 v[62:63], v[28:29], off
	v_pk_mul_f32 v[26:27], v[26:27], v[52:53] op_sel_hi:[1,0]
	v_pk_mul_f32 v[24:25], v[24:25], v[52:53] op_sel_hi:[1,0]
	v_pk_mul_f32 v[26:27], v[76:77], v[26:27]
	v_pk_mul_f32 v[24:25], v[74:75], v[24:25]
	v_pk_add_f32 v[90:91], v[90:91], 1.0 op_sel_hi:[1,0]
	v_pk_add_f32 v[92:93], v[92:93], 1.0 op_sel_hi:[1,0]
	v_pk_fma_f32 v[24:25], v[90:91], v[24:25], v[106:107]
	v_pk_fma_f32 v[26:27], v[92:93], v[26:27], v[108:109]
	v_cvt_pk_bf16_f32 v24, v24, v25
	v_cvt_pk_bf16_f32 v25, v26, v27
	global_store_dwordx2 v[62:63], v[24:25], off offset:512
	v_pk_mul_f32 v[22:23], v[22:23], v[52:53] op_sel_hi:[1,0]
	v_pk_mul_f32 v[20:21], v[20:21], v[52:53] op_sel_hi:[1,0]
	v_pk_mul_f32 v[22:23], v[80:81], v[22:23]
	v_pk_mul_f32 v[20:21], v[78:79], v[20:21]
	v_pk_add_f32 v[94:95], v[94:95], 1.0 op_sel_hi:[1,0]
	v_pk_add_f32 v[96:97], v[96:97], 1.0 op_sel_hi:[1,0]
	v_pk_fma_f32 v[20:21], v[94:95], v[20:21], v[110:111]
	v_pk_fma_f32 v[22:23], v[96:97], v[22:23], v[112:113]
	v_cvt_pk_bf16_f32 v20, v20, v21
	v_cvt_pk_bf16_f32 v21, v22, v23
	global_store_dwordx2 v[62:63], v[20:21], off offset:1024
	v_pk_mul_f32 v[18:19], v[18:19], v[52:53] op_sel_hi:[1,0]
	v_pk_mul_f32 v[16:17], v[16:17], v[52:53] op_sel_hi:[1,0]
	v_pk_mul_f32 v[18:19], v[84:85], v[18:19]
	v_pk_mul_f32 v[16:17], v[82:83], v[16:17]
	v_pk_add_f32 v[98:99], v[98:99], 1.0 op_sel_hi:[1,0]
	v_pk_add_f32 v[100:101], v[100:101], 1.0 op_sel_hi:[1,0]
	v_pk_fma_f32 v[16:17], v[98:99], v[16:17], v[114:115]
	v_pk_fma_f32 v[18:19], v[100:101], v[18:19], v[116:117]
	v_cvt_pk_bf16_f32 v16, v16, v17
	v_cvt_pk_bf16_f32 v17, v18, v19
	global_store_dwordx2 v[62:63], v[16:17], off offset:1536
	s_and_saveexec_b64 s[2:3], s[0:1]
	s_cbranch_execz .LBB0_1236
	v_mul_f32_e32 v47, v13, v13
	v_mul_f32_e32 v51, v15, v15
	v_fmac_f32_e32 v47, v12, v12
	v_fmac_f32_e32 v51, v14, v14
	v_add_f32_e32 v47, v47, v51
	v_mul_f32_e32 v49, v9, v9
	v_mul_f32_e32 v51, v11, v11
	v_fmac_f32_e32 v49, v8, v8
	v_fmac_f32_e32 v51, v10, v10
	v_add_f32_e32 v49, v49, v51
	v_add_f32_e32 v47, v47, v49
	v_mul_f32_e32 v49, v5, v5
	v_mul_f32_e32 v51, v7, v7
	v_fmac_f32_e32 v49, v4, v4
	v_fmac_f32_e32 v51, v6, v6
	v_add_f32_e32 v49, v49, v51
	v_add_f32_e32 v47, v47, v49
	v_mul_f32_e32 v49, v1, v1
	v_mul_f32_e32 v51, v3, v3
	v_fmac_f32_e32 v49, v0, v0
	v_fmac_f32_e32 v51, v2, v2
	v_add_f32_e32 v49, v49, v51
	v_add_f32_e32 v47, v47, v49
	s_nop 1
	v_add_f32_dpp v47, v47, v47 quad_perm:[1,0,3,2] row_mask:0xf bank_mask:0xf
	s_nop 1
	v_add_f32_dpp v47, v47, v47 quad_perm:[2,3,0,1] row_mask:0xf bank_mask:0xf
	s_nop 1
	v_add_f32_dpp v47, v47, v47 row_half_mirror row_mask:0xf bank_mask:0xf
	s_nop 1
	v_add_f32_dpp v47, v47, v47 row_mirror row_mask:0xf bank_mask:0xf
	v_mov_b32_e32 v49, v47
	s_nop 1
	v_permlane16_swap_b32_e32 v47, v49
	v_add_f32_e32 v47, v47, v49
	v_mov_b32_e32 v49, v47
	s_nop 1
	v_permlane32_swap_b32_e32 v47, v49
	v_add_f32_e32 v47, v47, v49
	v_fmamk_f32 v47, v47, 0x3a800000, v245
	s_mov_b32 s0, 0xf800000
	v_cmp_gt_f32_e32 vcc, s0, v47
	v_mul_f32_e32 v49, 0x4f800000, v47
	s_nop 0
	v_cndmask_b32_e32 v47, v47, v49, vcc
	v_sqrt_f32_e32 v49, v47
	s_nop 0
	v_add_u32_e32 v51, -1, v49
	v_fma_f32 v52, -v51, v49, v47
	v_cmp_ge_f32_e64 s[0:1], 0, v52
	v_add_u32_e32 v52, 1, v49
	s_nop 0
	v_cndmask_b32_e64 v51, v49, v51, s[0:1]
	v_fma_f32 v49, -v52, v49, v47
	v_cmp_lt_f32_e64 s[0:1], 0, v49
	s_nop 1
	v_cndmask_b32_e64 v49, v51, v52, s[0:1]
	v_mul_f32_e32 v51, 0x37800000, v49
	v_cndmask_b32_e32 v49, v49, v51, vcc
	v_cmp_class_f32_e32 vcc, v47, v250
	s_nop 1
	v_cndmask_b32_e32 v47, v49, v47, vcc
	v_div_scale_f32 v49, s[0:1], v47, v47, 1.0
	v_rcp_f32_e32 v51, v49
	s_nop 0
	v_fma_f32 v52, -v49, v51, 1.0
	v_fmac_f32_e32 v51, v52, v51
	v_div_scale_f32 v52, vcc, 1.0, v47, 1.0
	v_mul_f32_e32 v66, v52, v51
	v_fma_f32 v67, -v49, v66, v52
	v_fmac_f32_e32 v66, v67, v51
	v_fma_f32 v49, -v49, v66, v52
	v_div_fmas_f32 v49, v49, v51, v66
	v_div_fixup_f32 v52, v49, v47, 1.0
	v_pk_mul_f32 v[14:15], v[14:15], v[52:53] op_sel_hi:[1,0]
	v_pk_mul_f32 v[12:13], v[12:13], v[52:53] op_sel_hi:[1,0]
	v_pk_mul_f32 v[14:15], v[72:73], v[14:15]
	v_pk_mul_f32 v[12:13], v[70:71], v[12:13]
	v_pk_add_f32 v[118:119], v[118:119], 1.0 op_sel_hi:[1,0]
	v_pk_add_f32 v[120:121], v[120:121], 1.0 op_sel_hi:[1,0]
	v_pk_fma_f32 v[12:13], v[118:119], v[12:13], v[134:135]
	v_pk_fma_f32 v[14:15], v[120:121], v[14:15], v[136:137]
	v_cvt_pk_bf16_f32 v12, v12, v13
	v_cvt_pk_bf16_f32 v13, v14, v15
	global_store_dwordx2 v[64:65], v[12:13], off
	v_pk_mul_f32 v[10:11], v[10:11], v[52:53] op_sel_hi:[1,0]
	v_pk_mul_f32 v[8:9], v[8:9], v[52:53] op_sel_hi:[1,0]
	v_pk_mul_f32 v[10:11], v[76:77], v[10:11]
	v_pk_mul_f32 v[8:9], v[74:75], v[8:9]
	v_pk_add_f32 v[122:123], v[122:123], 1.0 op_sel_hi:[1,0]
	v_pk_add_f32 v[124:125], v[124:125], 1.0 op_sel_hi:[1,0]
	v_pk_fma_f32 v[8:9], v[122:123], v[8:9], v[138:139]
	v_pk_fma_f32 v[10:11], v[124:125], v[10:11], v[140:141]
	v_cvt_pk_bf16_f32 v8, v8, v9
	v_cvt_pk_bf16_f32 v9, v10, v11
	global_store_dwordx2 v[64:65], v[8:9], off offset:512
	v_pk_mul_f32 v[6:7], v[6:7], v[52:53] op_sel_hi:[1,0]
	v_pk_mul_f32 v[4:5], v[4:5], v[52:53] op_sel_hi:[1,0]
	v_pk_mul_f32 v[6:7], v[80:81], v[6:7]
	v_pk_mul_f32 v[4:5], v[78:79], v[4:5]
	v_pk_add_f32 v[126:127], v[126:127], 1.0 op_sel_hi:[1,0]
	v_pk_add_f32 v[128:129], v[128:129], 1.0 op_sel_hi:[1,0]
	v_pk_fma_f32 v[4:5], v[126:127], v[4:5], v[142:143]
	v_pk_fma_f32 v[6:7], v[128:129], v[6:7], v[144:145]
	v_cvt_pk_bf16_f32 v4, v4, v5
	v_cvt_pk_bf16_f32 v5, v6, v7
	global_store_dwordx2 v[64:65], v[4:5], off offset:1024
	v_pk_mul_f32 v[2:3], v[2:3], v[52:53] op_sel_hi:[1,0]
	v_pk_mul_f32 v[0:1], v[0:1], v[52:53] op_sel_hi:[1,0]
	v_pk_mul_f32 v[2:3], v[84:85], v[2:3]
	v_pk_mul_f32 v[0:1], v[82:83], v[0:1]
	v_pk_add_f32 v[130:131], v[130:131], 1.0 op_sel_hi:[1,0]
	v_pk_add_f32 v[132:133], v[132:133], 1.0 op_sel_hi:[1,0]
	v_pk_fma_f32 v[0:1], v[130:131], v[0:1], v[146:147]
	v_pk_fma_f32 v[2:3], v[132:133], v[2:3], v[148:149]
	v_cvt_pk_bf16_f32 v0, v0, v1
	v_cvt_pk_bf16_f32 v1, v2, v3
	global_store_dwordx2 v[64:65], v[0:1], off offset:1536
	s_branch .LBB0_1236

.LBB0_1473:
	s_or_b64 exec, exec, s[2:3]
	s_waitcnt vmcnt(3)
	v_mul_f32_e32 v42, v29, v29
	v_mul_f32_e32 v43, v31, v31
	v_fmac_f32_e32 v42, v28, v28
	v_fmac_f32_e32 v43, v30, v30
	v_add_f32_e32 v42, v42, v43
	s_waitcnt vmcnt(2)
	v_mul_f32_e32 v43, v25, v25
	v_mul_f32_e32 v44, v27, v27
	v_fmac_f32_e32 v43, v24, v24
	v_fmac_f32_e32 v44, v26, v26
	v_add_f32_e32 v43, v43, v44
	v_add_f32_e32 v46, v42, v43
	global_load_dwordx4 v[42:45], v[34:35], off
	s_waitcnt vmcnt(2)
	v_mul_f32_e32 v47, v21, v21
	v_mul_f32_e32 v48, v23, v23
	v_fmac_f32_e32 v47, v20, v20
	v_fmac_f32_e32 v48, v22, v22
	v_add_f32_e32 v47, v47, v48
	v_add_f32_e32 v46, v46, v47
	s_waitcnt vmcnt(1)
	v_mul_f32_e32 v47, v17, v17
	v_mul_f32_e32 v48, v19, v19
	v_fmac_f32_e32 v47, v16, v16
	v_fmac_f32_e32 v48, v18, v18
	v_add_f32_e32 v47, v47, v48
	v_add_f32_e32 v46, v46, v47
	s_nop 1
	v_add_f32_dpp v46, v46, v46 quad_perm:[1,0,3,2] row_mask:0xf bank_mask:0xf
	s_nop 1
	v_add_f32_dpp v46, v46, v46 quad_perm:[2,3,0,1] row_mask:0xf bank_mask:0xf
	s_nop 1
	v_add_f32_dpp v46, v46, v46 row_half_mirror row_mask:0xf bank_mask:0xf
	s_nop 1
	v_add_f32_dpp v46, v46, v46 row_mirror row_mask:0xf bank_mask:0xf
	v_mov_b32_e32 v47, v46
	s_nop 1
	v_permlane16_swap_b32_e32 v46, v47
	v_add_f32_e32 v46, v46, v47
	v_mov_b32_e32 v47, v46
	s_nop 1
	v_permlane32_swap_b32_e32 v46, v47
	v_add_f32_e32 v46, v46, v47
	v_fmamk_f32 v46, v46, 0x3a800000, v40
	v_mul_f32_e32 v47, 0x4f800000, v46
	v_cmp_gt_f32_e32 vcc, s7, v46
	s_nop 1
	v_cndmask_b32_e32 v46, v46, v47, vcc
	v_sqrt_f32_e32 v47, v46
	s_nop 0
	v_add_u32_e32 v48, -1, v47
	v_add_u32_e32 v49, 1, v47
	v_fma_f32 v50, -v48, v47, v46
	v_fma_f32 v51, -v49, v47, v46
	v_cmp_ge_f32_e64 s[2:3], 0, v50
	s_nop 1
	v_cndmask_b32_e64 v47, v47, v48, s[2:3]
	v_cmp_lt_f32_e64 s[2:3], 0, v51
	s_nop 1
	v_cndmask_b32_e64 v47, v47, v49, s[2:3]
	v_mul_f32_e32 v48, 0x37800000, v47
	v_cndmask_b32_e32 v47, v47, v48, vcc
	v_cmp_class_f32_e32 vcc, v46, v41
	s_nop 1
	v_cndmask_b32_e32 v46, v47, v46, vcc
	v_div_scale_f32 v47, s[2:3], v46, v46, 1.0
	v_rcp_f32_e32 v48, v47
	v_div_scale_f32 v49, vcc, 1.0, v46, 1.0
	v_fma_f32 v50, -v47, v48, 1.0
	v_fmac_f32_e32 v48, v50, v48
	v_mul_f32_e32 v50, v49, v48
	v_fma_f32 v51, -v47, v50, v49
	v_fmac_f32_e32 v50, v51, v48
	v_fma_f32 v47, -v47, v50, v49
	v_div_fmas_f32 v47, v47, v48, v50
	v_div_fixup_f32 v46, v47, v46, 1.0
	v_pk_mul_f32 v[28:29], v[28:29], v[46:47] op_sel_hi:[1,0]
	v_pk_mul_f32 v[30:31], v[30:31], v[46:47] op_sel_hi:[1,0]
	s_waitcnt vmcnt(0)
	v_pk_mul_f32 v[28:29], v[42:43], v[28:29]
	v_pk_mul_f32 v[30:31], v[44:45], v[30:31]
	global_store_dwordx4 v[38:39], v[28:31], off
	global_load_dwordx4 v[28:31], v[34:35], off offset:1024
	v_pk_mul_f32 v[26:27], v[26:27], v[46:47] op_sel_hi:[1,0]
	v_pk_mul_f32 v[24:25], v[24:25], v[46:47] op_sel_hi:[1,0]
	v_pk_mul_f32 v[22:23], v[22:23], v[46:47] op_sel_hi:[1,0]
	v_pk_mul_f32 v[20:21], v[20:21], v[46:47] op_sel_hi:[1,0]
	v_pk_mul_f32 v[18:19], v[18:19], v[46:47] op_sel_hi:[1,0]
	v_pk_mul_f32 v[16:17], v[16:17], v[46:47] op_sel_hi:[1,0]
	s_waitcnt vmcnt(0)
	v_pk_mul_f32 v[24:25], v[28:29], v[24:25]
	v_pk_mul_f32 v[26:27], v[30:31], v[26:27]
	global_store_dwordx4 v[38:39], v[24:27], off offset:1024
	global_load_dwordx4 v[24:27], v[34:35], off offset:2048
	s_waitcnt vmcnt(0)
	v_pk_mul_f32 v[20:21], v[24:25], v[20:21]
	v_pk_mul_f32 v[22:23], v[26:27], v[22:23]
	global_store_dwordx4 v[38:39], v[20:23], off offset:2048
	global_load_dwordx4 v[20:23], v[34:35], off offset:3072
	s_waitcnt vmcnt(0)
	v_pk_mul_f32 v[16:17], v[20:21], v[16:17]
	v_pk_mul_f32 v[18:19], v[22:23], v[18:19]
	global_store_dwordx4 v[38:39], v[16:19], off offset:3072
	s_and_saveexec_b64 s[2:3], s[0:1]
	s_cbranch_execz .LBB0_1470
	v_mul_f32_e32 v16, v13, v13
	v_mul_f32_e32 v17, v15, v15
	v_fmac_f32_e32 v16, v12, v12
	v_fmac_f32_e32 v17, v14, v14
	v_add_f32_e32 v16, v16, v17
	v_mul_f32_e32 v17, v9, v9
	v_mul_f32_e32 v18, v11, v11
	v_fmac_f32_e32 v17, v8, v8
	v_fmac_f32_e32 v18, v10, v10
	v_add_f32_e32 v17, v17, v18
	v_add_f32_e32 v20, v17, v16
	global_load_dwordx4 v[16:19], v[34:35], off
	v_mul_f32_e32 v21, v5, v5
	v_mul_f32_e32 v22, v7, v7
	v_fmac_f32_e32 v21, v4, v4
	v_fmac_f32_e32 v22, v6, v6
	v_add_f32_e32 v21, v21, v22
	v_add_f32_e32 v20, v21, v20
	v_mul_f32_e32 v21, v1, v1
	v_mul_f32_e32 v22, v3, v3
	v_fmac_f32_e32 v21, v0, v0
	v_fmac_f32_e32 v22, v2, v2
	v_add_f32_e32 v21, v21, v22
	v_add_f32_e32 v20, v21, v20
	s_nop 1
	v_add_f32_dpp v20, v20, v20 quad_perm:[1,0,3,2] row_mask:0xf bank_mask:0xf
	s_nop 1
	v_add_f32_dpp v20, v20, v20 quad_perm:[2,3,0,1] row_mask:0xf bank_mask:0xf
	s_nop 1
	v_add_f32_dpp v20, v20, v20 row_half_mirror row_mask:0xf bank_mask:0xf
	s_nop 1
	v_add_f32_dpp v20, v20, v20 row_mirror row_mask:0xf bank_mask:0xf
	v_mov_b32_e32 v21, v20
	s_nop 1
	v_permlane16_swap_b32_e32 v20, v21
	v_add_f32_e32 v20, v20, v21
	v_mov_b32_e32 v21, v20
	s_nop 1
	v_permlane32_swap_b32_e32 v20, v21
	v_add_f32_e32 v20, v20, v21
	v_fmamk_f32 v20, v20, 0x3a800000, v40
	v_mul_f32_e32 v21, 0x4f800000, v20
	v_cmp_gt_f32_e32 vcc, s7, v20
	s_nop 1
	v_cndmask_b32_e32 v22, v20, v21, vcc
	v_sqrt_f32_e32 v23, v22
	v_lshlrev_b64 v[20:21], 12, v[36:37]
	v_lshl_add_u64 v[20:21], v[32:33], 0, v[20:21]
	v_add_u32_e32 v24, -1, v23
	v_add_u32_e32 v25, 1, v23
	v_fma_f32 v26, -v24, v23, v22
	v_fma_f32 v27, -v25, v23, v22
	v_cmp_ge_f32_e64 s[0:1], 0, v26
	s_nop 1
	v_cndmask_b32_e64 v23, v23, v24, s[0:1]
	v_cmp_lt_f32_e64 s[0:1], 0, v27
	s_nop 1
	v_cndmask_b32_e64 v23, v23, v25, s[0:1]
	v_mul_f32_e32 v24, 0x37800000, v23
	v_cndmask_b32_e32 v23, v23, v24, vcc
	v_cmp_class_f32_e32 vcc, v22, v41
	s_nop 1
	v_cndmask_b32_e32 v22, v23, v22, vcc
	v_div_scale_f32 v23, s[0:1], v22, v22, 1.0
	v_rcp_f32_e32 v24, v23
	v_div_scale_f32 v25, vcc, 1.0, v22, 1.0
	v_fma_f32 v26, -v23, v24, 1.0
	v_fmac_f32_e32 v24, v26, v24
	v_mul_f32_e32 v26, v25, v24
	v_fma_f32 v27, -v23, v26, v25
	v_fmac_f32_e32 v26, v27, v24
	v_fma_f32 v23, -v23, v26, v25
	v_div_fmas_f32 v23, v23, v24, v26
	v_div_fixup_f32 v22, v23, v22, 1.0
	v_pk_mul_f32 v[24:25], v[12:13], v[22:23] op_sel_hi:[1,0]
	v_pk_mul_f32 v[26:27], v[14:15], v[22:23] op_sel_hi:[1,0]
	s_waitcnt vmcnt(0)
	v_pk_mul_f32 v[16:17], v[16:17], v[24:25]
	v_pk_mul_f32 v[18:19], v[18:19], v[26:27]
	global_store_dwordx4 v[20:21], v[16:19], off
	global_load_dwordx4 v[16:19], v[34:35], off offset:1024
	v_pk_mul_f32 v[24:25], v[10:11], v[22:23] op_sel_hi:[1,0]
	v_pk_mul_f32 v[26:27], v[8:9], v[22:23] op_sel_hi:[1,0]
	s_waitcnt vmcnt(0)
	v_pk_mul_f32 v[18:19], v[18:19], v[24:25]
	v_pk_mul_f32 v[16:17], v[16:17], v[26:27]
	global_store_dwordx4 v[20:21], v[16:19], off offset:1024
	global_load_dwordx4 v[16:19], v[34:35], off offset:2048
	v_pk_mul_f32 v[24:25], v[6:7], v[22:23] op_sel_hi:[1,0]
	v_pk_mul_f32 v[26:27], v[4:5], v[22:23] op_sel_hi:[1,0]
	s_waitcnt vmcnt(0)
	v_pk_mul_f32 v[18:19], v[18:19], v[24:25]
	v_pk_mul_f32 v[16:17], v[16:17], v[26:27]
	global_store_dwordx4 v[20:21], v[16:19], off offset:2048
	global_load_dwordx4 v[16:19], v[34:35], off offset:3072
	v_pk_mul_f32 v[24:25], v[2:3], v[22:23] op_sel_hi:[1,0]
	v_pk_mul_f32 v[22:23], v[0:1], v[22:23] op_sel_hi:[1,0]
	s_waitcnt vmcnt(0)
	v_pk_mul_f32 v[18:19], v[18:19], v[24:25]
	v_pk_mul_f32 v[16:17], v[16:17], v[22:23]
	global_store_dwordx4 v[20:21], v[16:19], off offset:3072
	s_branch .LBB0_1470
